# mini_ring consume rewrite extended to the six drain chunks of in-proj x2 and FFN-down sample units
# speedup vs baseline: 1.0196x; 1.0056x over previous
; #define MR_ISSUE(c) do { const unsigned sb_ = ldw + (unsigned)(((c) & (NS - 1)) * SLOT); glds16_m(src[0] + (size_t)(c) * 128, sb_); glds16_m(src[1] + (size_t)(c) * 128, sb_ + 8192u); } while (0)
; template <class Epi>
; __device__ __forceinline__ void mini_ring(PG8_LAS unsigned char* lds, const bf16_t* A, const bf16_t* Bt, int K, const Epi& E, int mu, int wave_u) {
;     ...
;     const int nmain = nchunk - PD;
; #pragma unroll 1
;     for (int c = 0; c < nmain; ++c) {
;         MR_ISSUE(c + PD);
;         asm volatile("s_waitcnt vmcnt(12)" ::: "memory"); __builtin_amdgcn_s_barrier(); asm volatile("" ::: "memory");
;         MR_CONSUME(c);
;     }
;     asm volatile("s_waitcnt vmcnt(10)" ::: "memory"); __builtin_amdgcn_s_barrier(); asm volatile("" ::: "memory"); MR_CONSUME(nmain);
;     asm volatile("s_waitcnt vmcnt(8)" ::: "memory"); __builtin_amdgcn_s_barrier(); asm volatile("" ::: "memory"); MR_CONSUME(nmain + 1);
;     asm volatile("s_waitcnt vmcnt(6)" ::: "memory"); __builtin_amdgcn_s_barrier(); asm volatile("" ::: "memory"); MR_CONSUME(nmain + 2);
;     asm volatile("s_waitcnt vmcnt(4)" ::: "memory"); __builtin_amdgcn_s_barrier(); asm volatile("" ::: "memory"); MR_CONSUME(nmain + 3);
.LBB0_203:
	s_waitcnt vmcnt(10)
	s_barrier
	v_add_u32_e32 v2, 0, v27
	v_add_u32_e32 v0, 0, v28
	s_and_b64 vcc, exec, s[16:17]
	v_add_u32_e32 v21, v2, v26
	v_add_u32_e32 v20, v2, v25
	v_add_u32_e32 v3, v0, v26
	v_add_u32_e32 v2, v0, v25
	s_cbranch_vccz .LBB0_205
	ds_read_b128 v[34:37], v21 offset:32768
	ds_read_b128 v[30:33], v3 offset:40960
	ds_read_b128 v[44:47], v3 offset:43008
	ds_read_b128 v[48:51], v3 offset:45056
	ds_read_b128 v[56:59], v3 offset:47104
	ds_read_b128 v[38:41], v20 offset:32768
	ds_read_b128 v[64:67], v2 offset:40960
	ds_read_b128 v[68:71], v2 offset:43008
	s_waitcnt lgkmcnt(6)
	v_mfma_f32_16x16x32_bf16 v[16:19], v[30:33], v[34:37], v[16:19]
	ds_read_b128 v[30:33], v2 offset:45056
	s_waitcnt lgkmcnt(6)
	v_mfma_f32_16x16x32_bf16 v[12:15], v[44:47], v[34:37], v[12:15]
	ds_read_b128 v[44:47], v2 offset:47104
	s_waitcnt lgkmcnt(6)
	v_mfma_f32_16x16x32_bf16 v[4:7], v[48:51], v[34:37], v[4:7]
	s_waitcnt lgkmcnt(5)
	v_mfma_f32_16x16x32_bf16 v[8:11], v[56:59], v[34:37], v[8:11]
	s_waitcnt lgkmcnt(3)
	v_mfma_f32_16x16x32_bf16 v[16:19], v[64:67], v[38:41], v[16:19]
	s_waitcnt lgkmcnt(2)
	v_mfma_f32_16x16x32_bf16 v[12:15], v[68:71], v[38:41], v[12:15]
	s_waitcnt lgkmcnt(1)
	v_mfma_f32_16x16x32_bf16 v[4:7], v[30:33], v[38:41], v[4:7]
	s_waitcnt lgkmcnt(0)
	v_mfma_f32_16x16x32_bf16 v[8:11], v[44:47], v[38:41], v[8:11]
.LBB0_205:
	s_waitcnt vmcnt(8)
	s_barrier
	s_and_b64 vcc, exec, s[10:11]
	s_cbranch_vccnz .LBB0_207
	ds_read_b128 v[34:37], v21 offset:49152
	ds_read_b128 v[30:33], v3 offset:57344
	ds_read_b128 v[44:47], v3 offset:59392
	ds_read_b128 v[48:51], v3 offset:61440
	ds_read_b128 v[56:59], v3 offset:63488
	ds_read_b128 v[38:41], v20 offset:49152
	ds_read_b128 v[64:67], v2 offset:57344
	ds_read_b128 v[68:71], v2 offset:59392
	s_waitcnt lgkmcnt(6)
	v_mfma_f32_16x16x32_bf16 v[16:19], v[30:33], v[34:37], v[16:19]
	ds_read_b128 v[30:33], v2 offset:61440
	s_waitcnt lgkmcnt(6)
	v_mfma_f32_16x16x32_bf16 v[12:15], v[44:47], v[34:37], v[12:15]
	ds_read_b128 v[44:47], v2 offset:63488
	s_waitcnt lgkmcnt(6)
	v_mfma_f32_16x16x32_bf16 v[4:7], v[48:51], v[34:37], v[4:7]
	s_waitcnt lgkmcnt(5)
	v_mfma_f32_16x16x32_bf16 v[8:11], v[56:59], v[34:37], v[8:11]
	s_waitcnt lgkmcnt(3)
	v_mfma_f32_16x16x32_bf16 v[16:19], v[64:67], v[38:41], v[16:19]
	s_waitcnt lgkmcnt(2)
	v_mfma_f32_16x16x32_bf16 v[12:15], v[68:71], v[38:41], v[12:15]
	s_waitcnt lgkmcnt(1)
	v_mfma_f32_16x16x32_bf16 v[4:7], v[30:33], v[38:41], v[4:7]
	s_waitcnt lgkmcnt(0)
	v_mfma_f32_16x16x32_bf16 v[8:11], v[44:47], v[38:41], v[8:11]
.LBB0_207:
	s_waitcnt vmcnt(6)
	s_barrier
	s_and_b64 vcc, exec, s[10:11]
	s_cbranch_vccnz .LBB0_209
	s_mov_b32 s0, 0x10000
	v_add_u32_e32 v29, s0, v3
	v_add_u32_e32 v0, s0, v2
	v_add_u32_e32 v22, s0, v21
	v_add_u32_e32 v23, s0, v20
	ds_read_b128 v[34:37], v22
	ds_read_b128 v[30:33], v29 offset:8192
	ds_read_b128 v[44:47], v29 offset:10240
	ds_read_b128 v[48:51], v29 offset:12288
	ds_read_b128 v[56:59], v29 offset:14336
	ds_read_b128 v[38:41], v23
	ds_read_b128 v[64:67], v0 offset:8192
	ds_read_b128 v[68:71], v0 offset:10240
	s_waitcnt lgkmcnt(6)
	v_mfma_f32_16x16x32_bf16 v[16:19], v[30:33], v[34:37], v[16:19]
	ds_read_b128 v[30:33], v0 offset:12288
	s_waitcnt lgkmcnt(6)
	v_mfma_f32_16x16x32_bf16 v[12:15], v[44:47], v[34:37], v[12:15]
	ds_read_b128 v[44:47], v0 offset:14336
	s_waitcnt lgkmcnt(6)
	v_mfma_f32_16x16x32_bf16 v[4:7], v[48:51], v[34:37], v[4:7]
	s_waitcnt lgkmcnt(5)
	v_mfma_f32_16x16x32_bf16 v[8:11], v[56:59], v[34:37], v[8:11]
	s_waitcnt lgkmcnt(3)
	v_mfma_f32_16x16x32_bf16 v[16:19], v[64:67], v[38:41], v[16:19]
	s_waitcnt lgkmcnt(2)
	v_mfma_f32_16x16x32_bf16 v[12:15], v[68:71], v[38:41], v[12:15]
	s_waitcnt lgkmcnt(1)
	v_mfma_f32_16x16x32_bf16 v[4:7], v[30:33], v[38:41], v[4:7]
	s_waitcnt lgkmcnt(0)
	v_mfma_f32_16x16x32_bf16 v[8:11], v[44:47], v[38:41], v[8:11]
; template <class Epi>
; __device__ __forceinline__ void mini_ring(PG8_LAS unsigned char* lds, const bf16_t* A, const bf16_t* Bt, int K, const Epi& E, int mu, int wave_u) {
;     ...
;     asm volatile("s_waitcnt vmcnt(10)" ::: "memory"); __builtin_amdgcn_s_barrier(); asm volatile("" ::: "memory"); MR_CONSUME(nmain);
;     asm volatile("s_waitcnt vmcnt(8)" ::: "memory"); __builtin_amdgcn_s_barrier(); asm volatile("" ::: "memory"); MR_CONSUME(nmain + 1);
;     asm volatile("s_waitcnt vmcnt(6)" ::: "memory"); __builtin_amdgcn_s_barrier(); asm volatile("" ::: "memory"); MR_CONSUME(nmain + 2);
;     asm volatile("s_waitcnt vmcnt(4)" ::: "memory"); __builtin_amdgcn_s_barrier(); asm volatile("" ::: "memory"); MR_CONSUME(nmain + 3);
;     asm volatile("s_waitcnt vmcnt(2)" ::: "memory"); __builtin_amdgcn_s_barrier(); asm volatile("" ::: "memory"); MR_CONSUME(nmain + 4);
;     asm volatile("s_waitcnt vmcnt(0)" ::: "memory"); __builtin_amdgcn_s_barrier(); asm volatile("" ::: "memory"); MR_CONSUME(nmain + 5);
.LBB0_209:
	s_waitcnt vmcnt(4)
	s_barrier
	s_and_b64 vcc, exec, s[10:11]
	s_cbranch_vccnz .LBB0_211
	s_mov_b32 s0, 0x14000
	v_add_u32_e32 v29, s0, v3
	v_add_u32_e32 v0, s0, v2
	v_add_u32_e32 v22, s0, v21
	v_add_u32_e32 v23, s0, v20
	ds_read_b128 v[34:37], v22
	ds_read_b128 v[30:33], v29 offset:8192
	ds_read_b128 v[44:47], v29 offset:10240
	ds_read_b128 v[48:51], v29 offset:12288
	ds_read_b128 v[56:59], v29 offset:14336
	ds_read_b128 v[38:41], v23
	ds_read_b128 v[64:67], v0 offset:8192
	ds_read_b128 v[68:71], v0 offset:10240
	s_waitcnt lgkmcnt(6)
	v_mfma_f32_16x16x32_bf16 v[16:19], v[30:33], v[34:37], v[16:19]
	ds_read_b128 v[30:33], v0 offset:12288
	s_waitcnt lgkmcnt(6)
	v_mfma_f32_16x16x32_bf16 v[12:15], v[44:47], v[34:37], v[12:15]
	ds_read_b128 v[44:47], v0 offset:14336
	s_waitcnt lgkmcnt(6)
	v_mfma_f32_16x16x32_bf16 v[4:7], v[48:51], v[34:37], v[4:7]
	s_waitcnt lgkmcnt(5)
	v_mfma_f32_16x16x32_bf16 v[8:11], v[56:59], v[34:37], v[8:11]
	s_waitcnt lgkmcnt(3)
	v_mfma_f32_16x16x32_bf16 v[16:19], v[64:67], v[38:41], v[16:19]
	s_waitcnt lgkmcnt(2)
	v_mfma_f32_16x16x32_bf16 v[12:15], v[68:71], v[38:41], v[12:15]
	s_waitcnt lgkmcnt(1)
	v_mfma_f32_16x16x32_bf16 v[4:7], v[30:33], v[38:41], v[4:7]
	s_waitcnt lgkmcnt(0)
	v_mfma_f32_16x16x32_bf16 v[8:11], v[44:47], v[38:41], v[8:11]
.LBB0_211:
	s_waitcnt vmcnt(2)
	s_barrier
	s_and_b64 vcc, exec, s[10:11]
	s_cbranch_vccnz .LBB0_213
	s_mov_b32 s0, 0x18000
	v_add_u32_e32 v29, s0, v3
	v_add_u32_e32 v0, s0, v2
	v_add_u32_e32 v22, s0, v21
	v_add_u32_e32 v23, s0, v20
	ds_read_b128 v[34:37], v22
	ds_read_b128 v[30:33], v29 offset:8192
	ds_read_b128 v[44:47], v29 offset:10240
	ds_read_b128 v[48:51], v29 offset:12288
	ds_read_b128 v[56:59], v29 offset:14336
	ds_read_b128 v[38:41], v23
	ds_read_b128 v[64:67], v0 offset:8192
	ds_read_b128 v[68:71], v0 offset:10240
	s_waitcnt lgkmcnt(6)
	v_mfma_f32_16x16x32_bf16 v[16:19], v[30:33], v[34:37], v[16:19]
	ds_read_b128 v[30:33], v0 offset:12288
	s_waitcnt lgkmcnt(6)
	v_mfma_f32_16x16x32_bf16 v[12:15], v[44:47], v[34:37], v[12:15]
	ds_read_b128 v[44:47], v0 offset:14336
	s_waitcnt lgkmcnt(6)
	v_mfma_f32_16x16x32_bf16 v[4:7], v[48:51], v[34:37], v[4:7]
	s_waitcnt lgkmcnt(5)
	v_mfma_f32_16x16x32_bf16 v[8:11], v[56:59], v[34:37], v[8:11]
	s_waitcnt lgkmcnt(3)
	v_mfma_f32_16x16x32_bf16 v[16:19], v[64:67], v[38:41], v[16:19]
	s_waitcnt lgkmcnt(2)
	v_mfma_f32_16x16x32_bf16 v[12:15], v[68:71], v[38:41], v[12:15]
	s_waitcnt lgkmcnt(1)
	v_mfma_f32_16x16x32_bf16 v[4:7], v[30:33], v[38:41], v[4:7]
	s_waitcnt lgkmcnt(0)
	v_mfma_f32_16x16x32_bf16 v[8:11], v[44:47], v[38:41], v[8:11]
.LBB0_213:
	s_waitcnt vmcnt(0)
	s_barrier
	s_and_b64 vcc, exec, s[10:11]
	s_cbranch_vccnz .LBB0_215
	s_mov_b32 s0, 0x1c000
	v_add_u32_e32 v29, s0, v3
	v_add_u32_e32 v0, s0, v2
	v_add_u32_e32 v22, s0, v21
	v_add_u32_e32 v23, s0, v20
	ds_read_b128 v[34:37], v22
	ds_read_b128 v[30:33], v29 offset:8192
	ds_read_b128 v[44:47], v29 offset:10240
	ds_read_b128 v[48:51], v29 offset:12288
	ds_read_b128 v[56:59], v29 offset:14336
	ds_read_b128 v[38:41], v23
	ds_read_b128 v[64:67], v0 offset:8192
	ds_read_b128 v[68:71], v0 offset:10240
	s_waitcnt lgkmcnt(6)
	v_mfma_f32_16x16x32_bf16 v[16:19], v[30:33], v[34:37], v[16:19]
	ds_read_b128 v[30:33], v0 offset:12288
	s_waitcnt lgkmcnt(6)
	v_mfma_f32_16x16x32_bf16 v[12:15], v[44:47], v[34:37], v[12:15]
	ds_read_b128 v[44:47], v0 offset:14336
	s_waitcnt lgkmcnt(6)
	v_mfma_f32_16x16x32_bf16 v[4:7], v[48:51], v[34:37], v[4:7]
	s_waitcnt lgkmcnt(5)
	v_mfma_f32_16x16x32_bf16 v[8:11], v[56:59], v[34:37], v[8:11]
	s_waitcnt lgkmcnt(3)
	v_mfma_f32_16x16x32_bf16 v[16:19], v[64:67], v[38:41], v[16:19]
	s_waitcnt lgkmcnt(2)
	v_mfma_f32_16x16x32_bf16 v[12:15], v[68:71], v[38:41], v[12:15]
	s_waitcnt lgkmcnt(1)
	v_mfma_f32_16x16x32_bf16 v[4:7], v[30:33], v[38:41], v[4:7]
	s_waitcnt lgkmcnt(0)
	v_mfma_f32_16x16x32_bf16 v[8:11], v[44:47], v[38:41], v[8:11]

; template <class Epi>
; __device__ __forceinline__ void mini_ring(PG8_LAS unsigned char* lds, const bf16_t* A, const bf16_t* Bt, int K, const Epi& E, int mu, int wave_u) {
;     ...
;     asm volatile("s_waitcnt vmcnt(10)" ::: "memory"); __builtin_amdgcn_s_barrier(); asm volatile("" ::: "memory"); MR_CONSUME(nmain);
;     asm volatile("s_waitcnt vmcnt(8)" ::: "memory"); __builtin_amdgcn_s_barrier(); asm volatile("" ::: "memory"); MR_CONSUME(nmain + 1);
;     asm volatile("s_waitcnt vmcnt(6)" ::: "memory"); __builtin_amdgcn_s_barrier(); asm volatile("" ::: "memory"); MR_CONSUME(nmain + 2);
;     asm volatile("s_waitcnt vmcnt(4)" ::: "memory"); __builtin_amdgcn_s_barrier(); asm volatile("" ::: "memory"); MR_CONSUME(nmain + 3);
;     asm volatile("s_waitcnt vmcnt(2)" ::: "memory"); __builtin_amdgcn_s_barrier(); asm volatile("" ::: "memory"); MR_CONSUME(nmain + 4);
;     asm volatile("s_waitcnt vmcnt(0)" ::: "memory"); __builtin_amdgcn_s_barrier(); asm volatile("" ::: "memory"); MR_CONSUME(nmain + 5);
.LBB0_353:
	s_waitcnt vmcnt(10)
	s_barrier
	v_add_u32_e32 v2, 0, v19
	v_add_u32_e32 v0, 0, v20
	s_and_b64 vcc, exec, s[14:15]
	v_add_u32_e32 v13, v2, v18
	v_add_u32_e32 v12, v2, v17
	v_add_u32_e32 v3, v0, v18
	v_add_u32_e32 v2, v0, v17
	s_cbranch_vccz .LBB0_355
	ds_read_b128 v[32:35], v13 offset:32768
	ds_read_b128 v[22:25], v3 offset:40960
	ds_read_b128 v[40:43], v3 offset:43008
	ds_read_b128 v[44:47], v3 offset:45056
	ds_read_b128 v[64:67], v3 offset:47104
	ds_read_b128 v[36:39], v12 offset:32768
	s_waitcnt lgkmcnt(4)
	v_mfma_f32_16x16x32_bf16 v[48:51], v[22:25], v[32:35], v[48:51]
	ds_read_b128 v[22:25], v2 offset:40960
	s_waitcnt lgkmcnt(4)
	v_mfma_f32_16x16x32_bf16 v[28:31], v[40:43], v[32:35], v[28:31]
	ds_read_b128 v[40:43], v2 offset:43008
	s_waitcnt lgkmcnt(4)
	v_mfma_f32_16x16x32_bf16 v[4:7], v[44:47], v[32:35], v[4:7]
	ds_read_b128 v[44:47], v2 offset:45056
	s_waitcnt lgkmcnt(4)
	v_mfma_f32_16x16x32_bf16 v[8:11], v[64:67], v[32:35], v[8:11]
	ds_read_b128 v[64:67], v2 offset:47104
	s_waitcnt lgkmcnt(3)
	v_mfma_f32_16x16x32_bf16 v[48:51], v[22:25], v[36:39], v[48:51]
	s_waitcnt lgkmcnt(2)
	v_mfma_f32_16x16x32_bf16 v[28:31], v[40:43], v[36:39], v[28:31]
	s_waitcnt lgkmcnt(1)
	v_mfma_f32_16x16x32_bf16 v[4:7], v[44:47], v[36:39], v[4:7]
	s_waitcnt lgkmcnt(0)
	v_mfma_f32_16x16x32_bf16 v[8:11], v[64:67], v[36:39], v[8:11]
.LBB0_355:
	s_waitcnt vmcnt(8)
	s_barrier
	s_and_b64 vcc, exec, s[10:11]
	s_cbranch_vccnz .LBB0_357
	ds_read_b128 v[32:35], v13 offset:49152
	ds_read_b128 v[22:25], v3 offset:57344
	ds_read_b128 v[40:43], v3 offset:59392
	ds_read_b128 v[44:47], v3 offset:61440
	ds_read_b128 v[64:67], v3 offset:63488
	ds_read_b128 v[36:39], v12 offset:49152
	s_waitcnt lgkmcnt(4)
	v_mfma_f32_16x16x32_bf16 v[48:51], v[22:25], v[32:35], v[48:51]
	ds_read_b128 v[22:25], v2 offset:57344
	s_waitcnt lgkmcnt(4)
	v_mfma_f32_16x16x32_bf16 v[28:31], v[40:43], v[32:35], v[28:31]
	ds_read_b128 v[40:43], v2 offset:59392
	s_waitcnt lgkmcnt(4)
	v_mfma_f32_16x16x32_bf16 v[4:7], v[44:47], v[32:35], v[4:7]
	ds_read_b128 v[44:47], v2 offset:61440
	s_waitcnt lgkmcnt(4)
	v_mfma_f32_16x16x32_bf16 v[8:11], v[64:67], v[32:35], v[8:11]
	ds_read_b128 v[64:67], v2 offset:63488
	s_waitcnt lgkmcnt(3)
	v_mfma_f32_16x16x32_bf16 v[48:51], v[22:25], v[36:39], v[48:51]
	s_waitcnt lgkmcnt(2)
	v_mfma_f32_16x16x32_bf16 v[28:31], v[40:43], v[36:39], v[28:31]
	s_waitcnt lgkmcnt(1)
	v_mfma_f32_16x16x32_bf16 v[4:7], v[44:47], v[36:39], v[4:7]
	s_waitcnt lgkmcnt(0)
	v_mfma_f32_16x16x32_bf16 v[8:11], v[64:67], v[36:39], v[8:11]
.LBB0_357:
	s_waitcnt vmcnt(6)
	s_barrier
	s_and_b64 vcc, exec, s[10:11]
	s_cbranch_vccnz .LBB0_359
	s_mov_b32 s0, 0x10000
	v_add_u32_e32 v21, s0, v3
	v_add_u32_e32 v0, s0, v2
	v_add_u32_e32 v14, s0, v13
	v_add_u32_e32 v15, s0, v12
	ds_read_b128 v[32:35], v14
	ds_read_b128 v[22:25], v21 offset:8192
	ds_read_b128 v[40:43], v21 offset:10240
	ds_read_b128 v[44:47], v21 offset:12288
	ds_read_b128 v[64:67], v21 offset:14336
	ds_read_b128 v[36:39], v15
	s_waitcnt lgkmcnt(4)
	v_mfma_f32_16x16x32_bf16 v[48:51], v[22:25], v[32:35], v[48:51]
	ds_read_b128 v[22:25], v0 offset:8192
	s_waitcnt lgkmcnt(4)
	v_mfma_f32_16x16x32_bf16 v[28:31], v[40:43], v[32:35], v[28:31]
	ds_read_b128 v[40:43], v0 offset:10240
	s_waitcnt lgkmcnt(4)
	v_mfma_f32_16x16x32_bf16 v[4:7], v[44:47], v[32:35], v[4:7]
	ds_read_b128 v[44:47], v0 offset:12288
	s_waitcnt lgkmcnt(4)
	v_mfma_f32_16x16x32_bf16 v[8:11], v[64:67], v[32:35], v[8:11]
	ds_read_b128 v[64:67], v0 offset:14336
	s_waitcnt lgkmcnt(3)
	v_mfma_f32_16x16x32_bf16 v[48:51], v[22:25], v[36:39], v[48:51]
	s_waitcnt lgkmcnt(2)
	v_mfma_f32_16x16x32_bf16 v[28:31], v[40:43], v[36:39], v[28:31]
	s_waitcnt lgkmcnt(1)
	v_mfma_f32_16x16x32_bf16 v[4:7], v[44:47], v[36:39], v[4:7]
	s_waitcnt lgkmcnt(0)
	v_mfma_f32_16x16x32_bf16 v[8:11], v[64:67], v[36:39], v[8:11]
; template <class Epi>
; __device__ __forceinline__ void mini_ring(PG8_LAS unsigned char* lds, const bf16_t* A, const bf16_t* Bt, int K, const Epi& E, int mu, int wave_u) {
;     ...
;     asm volatile("s_waitcnt vmcnt(10)" ::: "memory"); __builtin_amdgcn_s_barrier(); asm volatile("" ::: "memory"); MR_CONSUME(nmain);
;     asm volatile("s_waitcnt vmcnt(8)" ::: "memory"); __builtin_amdgcn_s_barrier(); asm volatile("" ::: "memory"); MR_CONSUME(nmain + 1);
;     asm volatile("s_waitcnt vmcnt(6)" ::: "memory"); __builtin_amdgcn_s_barrier(); asm volatile("" ::: "memory"); MR_CONSUME(nmain + 2);
;     asm volatile("s_waitcnt vmcnt(4)" ::: "memory"); __builtin_amdgcn_s_barrier(); asm volatile("" ::: "memory"); MR_CONSUME(nmain + 3);
;     asm volatile("s_waitcnt vmcnt(2)" ::: "memory"); __builtin_amdgcn_s_barrier(); asm volatile("" ::: "memory"); MR_CONSUME(nmain + 4);
;     asm volatile("s_waitcnt vmcnt(0)" ::: "memory"); __builtin_amdgcn_s_barrier(); asm volatile("" ::: "memory"); MR_CONSUME(nmain + 5);
.LBB0_359:
	s_waitcnt vmcnt(4)
	s_barrier
	s_and_b64 vcc, exec, s[10:11]
	s_cbranch_vccnz .LBB0_361
	s_mov_b32 s0, 0x14000
	v_add_u32_e32 v21, s0, v3
	v_add_u32_e32 v0, s0, v2
	v_add_u32_e32 v14, s0, v13
	v_add_u32_e32 v15, s0, v12
	ds_read_b128 v[32:35], v14
	ds_read_b128 v[22:25], v21 offset:8192
	ds_read_b128 v[40:43], v21 offset:10240
	ds_read_b128 v[44:47], v21 offset:12288
	ds_read_b128 v[64:67], v21 offset:14336
	ds_read_b128 v[36:39], v15
	s_waitcnt lgkmcnt(4)
	v_mfma_f32_16x16x32_bf16 v[48:51], v[22:25], v[32:35], v[48:51]
	ds_read_b128 v[22:25], v0 offset:8192
	s_waitcnt lgkmcnt(4)
	v_mfma_f32_16x16x32_bf16 v[28:31], v[40:43], v[32:35], v[28:31]
	ds_read_b128 v[40:43], v0 offset:10240
	s_waitcnt lgkmcnt(4)
	v_mfma_f32_16x16x32_bf16 v[4:7], v[44:47], v[32:35], v[4:7]
	ds_read_b128 v[44:47], v0 offset:12288
	s_waitcnt lgkmcnt(4)
	v_mfma_f32_16x16x32_bf16 v[8:11], v[64:67], v[32:35], v[8:11]
	ds_read_b128 v[64:67], v0 offset:14336
	s_waitcnt lgkmcnt(3)
	v_mfma_f32_16x16x32_bf16 v[48:51], v[22:25], v[36:39], v[48:51]
	s_waitcnt lgkmcnt(2)
	v_mfma_f32_16x16x32_bf16 v[28:31], v[40:43], v[36:39], v[28:31]
	s_waitcnt lgkmcnt(1)
	v_mfma_f32_16x16x32_bf16 v[4:7], v[44:47], v[36:39], v[4:7]
	s_waitcnt lgkmcnt(0)
	v_mfma_f32_16x16x32_bf16 v[8:11], v[64:67], v[36:39], v[8:11]
.LBB0_361:
	s_waitcnt vmcnt(2)
	s_barrier
	s_and_b64 vcc, exec, s[10:11]
	s_cbranch_vccnz .LBB0_363
	s_mov_b32 s0, 0x18000
	v_add_u32_e32 v21, s0, v3
	v_add_u32_e32 v0, s0, v2
	v_add_u32_e32 v14, s0, v13
	v_add_u32_e32 v15, s0, v12
	ds_read_b128 v[32:35], v14
	ds_read_b128 v[22:25], v21 offset:8192
	ds_read_b128 v[40:43], v21 offset:10240
	ds_read_b128 v[44:47], v21 offset:12288
	ds_read_b128 v[64:67], v21 offset:14336
	ds_read_b128 v[36:39], v15
	s_waitcnt lgkmcnt(4)
	v_mfma_f32_16x16x32_bf16 v[48:51], v[22:25], v[32:35], v[48:51]
	ds_read_b128 v[22:25], v0 offset:8192
	s_waitcnt lgkmcnt(4)
	v_mfma_f32_16x16x32_bf16 v[28:31], v[40:43], v[32:35], v[28:31]
	ds_read_b128 v[40:43], v0 offset:10240
	s_waitcnt lgkmcnt(4)
	v_mfma_f32_16x16x32_bf16 v[4:7], v[44:47], v[32:35], v[4:7]
	ds_read_b128 v[44:47], v0 offset:12288
	s_waitcnt lgkmcnt(4)
	v_mfma_f32_16x16x32_bf16 v[8:11], v[64:67], v[32:35], v[8:11]
	ds_read_b128 v[64:67], v0 offset:14336
	s_waitcnt lgkmcnt(3)
	v_mfma_f32_16x16x32_bf16 v[48:51], v[22:25], v[36:39], v[48:51]
	s_waitcnt lgkmcnt(2)
	v_mfma_f32_16x16x32_bf16 v[28:31], v[40:43], v[36:39], v[28:31]
	s_waitcnt lgkmcnt(1)
	v_mfma_f32_16x16x32_bf16 v[4:7], v[44:47], v[36:39], v[4:7]
	s_waitcnt lgkmcnt(0)
	v_mfma_f32_16x16x32_bf16 v[8:11], v[64:67], v[36:39], v[8:11]
.LBB0_363:
	s_waitcnt vmcnt(0)
	s_barrier
	s_and_b64 vcc, exec, s[10:11]
	s_cbranch_vccnz .LBB0_365
	s_mov_b32 s0, 0x1c000
	v_add_u32_e32 v21, s0, v3
	v_add_u32_e32 v0, s0, v2
	v_add_u32_e32 v14, s0, v13
	v_add_u32_e32 v15, s0, v12
	ds_read_b128 v[32:35], v14
	ds_read_b128 v[22:25], v21 offset:8192
	ds_read_b128 v[40:43], v21 offset:10240
	ds_read_b128 v[44:47], v21 offset:12288
	ds_read_b128 v[64:67], v21 offset:14336
	ds_read_b128 v[36:39], v15
	s_waitcnt lgkmcnt(4)
	v_mfma_f32_16x16x32_bf16 v[48:51], v[22:25], v[32:35], v[48:51]
	ds_read_b128 v[22:25], v0 offset:8192
	s_waitcnt lgkmcnt(4)
	v_mfma_f32_16x16x32_bf16 v[28:31], v[40:43], v[32:35], v[28:31]
	ds_read_b128 v[40:43], v0 offset:10240
	s_waitcnt lgkmcnt(4)
	v_mfma_f32_16x16x32_bf16 v[4:7], v[44:47], v[32:35], v[4:7]
	ds_read_b128 v[44:47], v0 offset:12288
	s_waitcnt lgkmcnt(4)
	v_mfma_f32_16x16x32_bf16 v[8:11], v[64:67], v[32:35], v[8:11]
	ds_read_b128 v[64:67], v0 offset:14336
	s_waitcnt lgkmcnt(3)
	v_mfma_f32_16x16x32_bf16 v[48:51], v[22:25], v[36:39], v[48:51]
	s_waitcnt lgkmcnt(2)
	v_mfma_f32_16x16x32_bf16 v[28:31], v[40:43], v[36:39], v[28:31]
	s_waitcnt lgkmcnt(1)
	v_mfma_f32_16x16x32_bf16 v[4:7], v[44:47], v[36:39], v[4:7]
	s_waitcnt lgkmcnt(0)
	v_mfma_f32_16x16x32_bf16 v[8:11], v[64:67], v[36:39], v[8:11]

; template <class Epi>
; __device__ __forceinline__ void mini_ring(PG8_LAS unsigned char* lds, const bf16_t* A, const bf16_t* Bt, int K, const Epi& E, int mu, int wave_u) {
;     ...
;     asm volatile("s_waitcnt vmcnt(10)" ::: "memory"); __builtin_amdgcn_s_barrier(); asm volatile("" ::: "memory"); MR_CONSUME(nmain);
;     asm volatile("s_waitcnt vmcnt(8)" ::: "memory"); __builtin_amdgcn_s_barrier(); asm volatile("" ::: "memory"); MR_CONSUME(nmain + 1);
;     asm volatile("s_waitcnt vmcnt(6)" ::: "memory"); __builtin_amdgcn_s_barrier(); asm volatile("" ::: "memory"); MR_CONSUME(nmain + 2);
;     asm volatile("s_waitcnt vmcnt(4)" ::: "memory"); __builtin_amdgcn_s_barrier(); asm volatile("" ::: "memory"); MR_CONSUME(nmain + 3);
;     asm volatile("s_waitcnt vmcnt(2)" ::: "memory"); __builtin_amdgcn_s_barrier(); asm volatile("" ::: "memory"); MR_CONSUME(nmain + 4);
;     asm volatile("s_waitcnt vmcnt(0)" ::: "memory"); __builtin_amdgcn_s_barrier(); asm volatile("" ::: "memory"); MR_CONSUME(nmain + 5);
.LBB0_1470:
	s_waitcnt vmcnt(10)
	s_barrier
	s_and_b64 vcc, exec, s[12:13]
	s_cbranch_vccz .LBB0_1472
	s_mov_b32 s0, 0x18000
	v_add_u32_e32 v0, s0, v12
	v_add_u32_e32 v6, v0, v9
	v_add_u32_e32 v7, s0, v11
	v_add_u32_e32 v13, v7, v9
	v_add_u32_e32 v0, v0, v10
	v_add_u32_e32 v7, v7, v10
	ds_read_b128 v[44:47], v13
	ds_read_b128 v[48:51], v6 offset:8192
	ds_read_b128 v[52:55], v6 offset:10240
	ds_read_b128 v[56:59], v6 offset:12288
	ds_read_b128 v[60:63], v6 offset:14336
	ds_read_b128 v[64:67], v7
	ds_read_b128 v[68:71], v0 offset:8192
	ds_read_b128 v[72:75], v0 offset:10240
	ds_read_b128 v[76:79], v0 offset:12288
	ds_read_b128 v[14:17], v0 offset:14336
	s_waitcnt lgkmcnt(8)
	v_mfma_f32_16x16x32_bf16 v[30:33], v[48:51], v[44:47], v[30:33]
	s_waitcnt lgkmcnt(7)
	v_mfma_f32_16x16x32_bf16 v[34:37], v[52:55], v[44:47], v[34:37]
	s_waitcnt lgkmcnt(6)
	v_mfma_f32_16x16x32_bf16 v[18:21], v[56:59], v[44:47], v[18:21]
	s_waitcnt lgkmcnt(5)
	v_mfma_f32_16x16x32_bf16 v[22:25], v[60:63], v[44:47], v[22:25]
	s_waitcnt lgkmcnt(3)
	v_mfma_f32_16x16x32_bf16 v[30:33], v[68:71], v[64:67], v[30:33]
	s_waitcnt lgkmcnt(2)
	v_mfma_f32_16x16x32_bf16 v[34:37], v[72:75], v[64:67], v[34:37]
	s_waitcnt lgkmcnt(1)
	v_mfma_f32_16x16x32_bf16 v[18:21], v[76:79], v[64:67], v[18:21]
	s_waitcnt lgkmcnt(0)
	v_mfma_f32_16x16x32_bf16 v[22:25], v[14:17], v[64:67], v[22:25]
.LBB0_1472:
	s_waitcnt vmcnt(8)
	s_barrier
	s_and_b64 vcc, exec, s[10:11]
	s_cbranch_vccnz .LBB0_1474
	s_mov_b32 s0, 0x1c000
	v_add_u32_e32 v0, s0, v12
	v_add_u32_e32 v6, v0, v9
	v_add_u32_e32 v7, s0, v11
	v_add_u32_e32 v13, v7, v9
	v_add_u32_e32 v0, v0, v10
	v_add_u32_e32 v7, v7, v10
	ds_read_b128 v[44:47], v13
	ds_read_b128 v[48:51], v6 offset:8192
	ds_read_b128 v[52:55], v6 offset:10240
	ds_read_b128 v[56:59], v6 offset:12288
	ds_read_b128 v[60:63], v6 offset:14336
	ds_read_b128 v[64:67], v7
	ds_read_b128 v[68:71], v0 offset:8192
	ds_read_b128 v[72:75], v0 offset:10240
	ds_read_b128 v[76:79], v0 offset:12288
	ds_read_b128 v[14:17], v0 offset:14336
	s_waitcnt lgkmcnt(8)
	v_mfma_f32_16x16x32_bf16 v[30:33], v[48:51], v[44:47], v[30:33]
	s_waitcnt lgkmcnt(7)
	v_mfma_f32_16x16x32_bf16 v[34:37], v[52:55], v[44:47], v[34:37]
	s_waitcnt lgkmcnt(6)
	v_mfma_f32_16x16x32_bf16 v[18:21], v[56:59], v[44:47], v[18:21]
	s_waitcnt lgkmcnt(5)
	v_mfma_f32_16x16x32_bf16 v[22:25], v[60:63], v[44:47], v[22:25]
	s_waitcnt lgkmcnt(3)
	v_mfma_f32_16x16x32_bf16 v[30:33], v[68:71], v[64:67], v[30:33]
	s_waitcnt lgkmcnt(2)
	v_mfma_f32_16x16x32_bf16 v[34:37], v[72:75], v[64:67], v[34:37]
	s_waitcnt lgkmcnt(1)
	v_mfma_f32_16x16x32_bf16 v[18:21], v[76:79], v[64:67], v[18:21]
	s_waitcnt lgkmcnt(0)
	v_mfma_f32_16x16x32_bf16 v[22:25], v[14:17], v[64:67], v[22:25]
.LBB0_1474:
	s_waitcnt vmcnt(6)
	s_barrier
	v_add_u32_e32 v0, 0, v11
	s_nop 2
	v_add_u32_e32 v5, 0, v12
	s_and_b64 vcc, exec, s[10:11]
	v_add_u32_e32 v4, v0, v9
	v_add_u32_e32 v3, v0, v10
	v_add_u32_e32 v2, v5, v9
	v_add_u32_e32 v0, v5, v10
	s_cbranch_vccnz .LBB0_1476
	ds_read_b128 v[44:47], v4
	ds_read_b128 v[48:51], v2 offset:8192
	ds_read_b128 v[52:55], v2 offset:10240
	ds_read_b128 v[56:59], v2 offset:12288
	ds_read_b128 v[60:63], v2 offset:14336
	ds_read_b128 v[64:67], v3
	ds_read_b128 v[68:71], v0 offset:8192
	ds_read_b128 v[72:75], v0 offset:10240
	ds_read_b128 v[76:79], v0 offset:12288
	ds_read_b128 v[14:17], v0 offset:14336
	s_waitcnt lgkmcnt(8)
	v_mfma_f32_16x16x32_bf16 v[30:33], v[48:51], v[44:47], v[30:33]
	s_waitcnt lgkmcnt(7)
	v_mfma_f32_16x16x32_bf16 v[34:37], v[52:55], v[44:47], v[34:37]
	s_waitcnt lgkmcnt(6)
	v_mfma_f32_16x16x32_bf16 v[18:21], v[56:59], v[44:47], v[18:21]
	s_waitcnt lgkmcnt(5)
	v_mfma_f32_16x16x32_bf16 v[22:25], v[60:63], v[44:47], v[22:25]
	s_waitcnt lgkmcnt(3)
	v_mfma_f32_16x16x32_bf16 v[30:33], v[68:71], v[64:67], v[30:33]
	s_waitcnt lgkmcnt(2)
	v_mfma_f32_16x16x32_bf16 v[34:37], v[72:75], v[64:67], v[34:37]
	s_waitcnt lgkmcnt(1)
	v_mfma_f32_16x16x32_bf16 v[18:21], v[76:79], v[64:67], v[18:21]
	s_waitcnt lgkmcnt(0)
	v_mfma_f32_16x16x32_bf16 v[22:25], v[14:17], v[64:67], v[22:25]
; template <class Epi>
; __device__ __forceinline__ void mini_ring(PG8_LAS unsigned char* lds, const bf16_t* A, const bf16_t* Bt, int K, const Epi& E, int mu, int wave_u) {
;     ...
;     asm volatile("s_waitcnt vmcnt(10)" ::: "memory"); __builtin_amdgcn_s_barrier(); asm volatile("" ::: "memory"); MR_CONSUME(nmain);
;     asm volatile("s_waitcnt vmcnt(8)" ::: "memory"); __builtin_amdgcn_s_barrier(); asm volatile("" ::: "memory"); MR_CONSUME(nmain + 1);
;     asm volatile("s_waitcnt vmcnt(6)" ::: "memory"); __builtin_amdgcn_s_barrier(); asm volatile("" ::: "memory"); MR_CONSUME(nmain + 2);
;     asm volatile("s_waitcnt vmcnt(4)" ::: "memory"); __builtin_amdgcn_s_barrier(); asm volatile("" ::: "memory"); MR_CONSUME(nmain + 3);
;     asm volatile("s_waitcnt vmcnt(2)" ::: "memory"); __builtin_amdgcn_s_barrier(); asm volatile("" ::: "memory"); MR_CONSUME(nmain + 4);
;     asm volatile("s_waitcnt vmcnt(0)" ::: "memory"); __builtin_amdgcn_s_barrier(); asm volatile("" ::: "memory"); MR_CONSUME(nmain + 5);
.LBB0_1476:
	s_waitcnt vmcnt(4)
	s_barrier
	s_and_b64 vcc, exec, s[10:11]
	s_cbranch_vccnz .LBB0_1478
	ds_read_b128 v[44:47], v4 offset:16384
	ds_read_b128 v[48:51], v2 offset:24576
	ds_read_b128 v[52:55], v2 offset:26624
	ds_read_b128 v[56:59], v2 offset:28672
	ds_read_b128 v[60:63], v2 offset:30720
	ds_read_b128 v[64:67], v3 offset:16384
	ds_read_b128 v[68:71], v0 offset:24576
	ds_read_b128 v[72:75], v0 offset:26624
	ds_read_b128 v[76:79], v0 offset:28672
	ds_read_b128 v[14:17], v0 offset:30720
	s_waitcnt lgkmcnt(8)
	v_mfma_f32_16x16x32_bf16 v[30:33], v[48:51], v[44:47], v[30:33]
	s_waitcnt lgkmcnt(7)
	v_mfma_f32_16x16x32_bf16 v[34:37], v[52:55], v[44:47], v[34:37]
	s_waitcnt lgkmcnt(6)
	v_mfma_f32_16x16x32_bf16 v[18:21], v[56:59], v[44:47], v[18:21]
	s_waitcnt lgkmcnt(5)
	v_mfma_f32_16x16x32_bf16 v[22:25], v[60:63], v[44:47], v[22:25]
	s_waitcnt lgkmcnt(3)
	v_mfma_f32_16x16x32_bf16 v[30:33], v[68:71], v[64:67], v[30:33]
	s_waitcnt lgkmcnt(2)
	v_mfma_f32_16x16x32_bf16 v[34:37], v[72:75], v[64:67], v[34:37]
	s_waitcnt lgkmcnt(1)
	v_mfma_f32_16x16x32_bf16 v[18:21], v[76:79], v[64:67], v[18:21]
	s_waitcnt lgkmcnt(0)
	v_mfma_f32_16x16x32_bf16 v[22:25], v[14:17], v[64:67], v[22:25]
.LBB0_1478:
	s_waitcnt vmcnt(2)
	s_barrier
	s_and_b64 vcc, exec, s[10:11]
	s_cbranch_vccnz .LBB0_1480
	ds_read_b128 v[44:47], v4 offset:32768
	ds_read_b128 v[48:51], v2 offset:40960
	ds_read_b128 v[52:55], v2 offset:43008
	ds_read_b128 v[56:59], v2 offset:45056
	ds_read_b128 v[60:63], v2 offset:47104
	ds_read_b128 v[64:67], v3 offset:32768
	ds_read_b128 v[68:71], v0 offset:40960
	ds_read_b128 v[72:75], v0 offset:43008
	ds_read_b128 v[76:79], v0 offset:45056
	ds_read_b128 v[14:17], v0 offset:47104
	s_waitcnt lgkmcnt(8)
	v_mfma_f32_16x16x32_bf16 v[30:33], v[48:51], v[44:47], v[30:33]
	s_waitcnt lgkmcnt(7)
	v_mfma_f32_16x16x32_bf16 v[34:37], v[52:55], v[44:47], v[34:37]
	s_waitcnt lgkmcnt(6)
	v_mfma_f32_16x16x32_bf16 v[18:21], v[56:59], v[44:47], v[18:21]
	s_waitcnt lgkmcnt(5)
	v_mfma_f32_16x16x32_bf16 v[22:25], v[60:63], v[44:47], v[22:25]
	s_waitcnt lgkmcnt(3)
	v_mfma_f32_16x16x32_bf16 v[30:33], v[68:71], v[64:67], v[30:33]
	s_waitcnt lgkmcnt(2)
	v_mfma_f32_16x16x32_bf16 v[34:37], v[72:75], v[64:67], v[34:37]
	s_waitcnt lgkmcnt(1)
	v_mfma_f32_16x16x32_bf16 v[18:21], v[76:79], v[64:67], v[18:21]
	s_waitcnt lgkmcnt(0)
	v_mfma_f32_16x16x32_bf16 v[22:25], v[14:17], v[64:67], v[22:25]
.LBB0_1480:
	s_waitcnt vmcnt(0)
	s_barrier
	s_and_b64 vcc, exec, s[10:11]
	s_cbranch_vccnz .LBB0_1482
	ds_read_b128 v[44:47], v4 offset:49152
	ds_read_b128 v[48:51], v2 offset:57344
	ds_read_b128 v[52:55], v2 offset:59392
	ds_read_b128 v[56:59], v2 offset:61440
	ds_read_b128 v[60:63], v2 offset:63488
	ds_read_b128 v[64:67], v3 offset:49152
	ds_read_b128 v[68:71], v0 offset:57344
	ds_read_b128 v[72:75], v0 offset:59392
	ds_read_b128 v[76:79], v0 offset:61440
	ds_read_b128 v[14:17], v0 offset:63488
	s_waitcnt lgkmcnt(8)
	v_mfma_f32_16x16x32_bf16 v[30:33], v[48:51], v[44:47], v[30:33]
	s_waitcnt lgkmcnt(7)
	v_mfma_f32_16x16x32_bf16 v[34:37], v[52:55], v[44:47], v[34:37]
	s_waitcnt lgkmcnt(6)
	v_mfma_f32_16x16x32_bf16 v[18:21], v[56:59], v[44:47], v[18:21]
	s_waitcnt lgkmcnt(5)
	v_mfma_f32_16x16x32_bf16 v[22:25], v[60:63], v[44:47], v[22:25]
	s_waitcnt lgkmcnt(3)
	v_mfma_f32_16x16x32_bf16 v[30:33], v[68:71], v[64:67], v[30:33]
	s_waitcnt lgkmcnt(2)
	v_mfma_f32_16x16x32_bf16 v[34:37], v[72:75], v[64:67], v[34:37]
	s_waitcnt lgkmcnt(1)
	v_mfma_f32_16x16x32_bf16 v[18:21], v[76:79], v[64:67], v[18:21]
	s_waitcnt lgkmcnt(0)
	v_mfma_f32_16x16x32_bf16 v[22:25], v[14:17], v[64:67], v[22:25]
